# mlstm_c: the tail's two o-gate row loads also issued at the item-loop top (own-row read-modify-write, no cross-item dependence)
# speedup vs baseline: 1.0090x; 1.0009x over previous
; __device__ __forceinline__ float sigmoidf_(float x) { return __builtin_amdgcn_rcpf(1.f + __expf(-x)); }
; __device__ __forceinline__ void phase_mlstm_c(const Args& a, unsigned char* lds) {
;     ...
;         { const int t = tid >> 3, part = tid & 7, dv0 = part * 16;
;             const float den = fmaxf(fabsf(denS[t]), __expf(-mtS[t])); const float inv = 1.f / den;
;             float hv[16]; float sq = 0.f;
; #pragma unroll
;             for (int e = 0; e < 16; ++e) { hv[e] = OUT[t * 132 + dv0 + e] * inv; sq += hv[e] * hv[e]; }
;             sq += __shfl_xor(sq, 1); sq += __shfl_xor(sq, 2); sq += __shfl_xor(sq, 4);
;             const float rs = rsqrtf(sq * (1.f / 128.f) + EPS);
;             bf16_t* po = P + (r0 + t) * LDP + C_MO + h * 128 + dv0;
;             float og[16]; unpack8(*(const u32x4*)po, og); unpack8(*(const u32x4*)(po + 8), og + 8);
; #pragma unroll
;             for (int e = 0; e < 16; ++e) hv[e] = hv[e] * rs * a.in[I_MHN][h * 128 + dv0 + e] * sigmoidf_(og[e]);
;             *(u32x4*)po = pack8(hv); *(u32x4*)(po + 8) = pack8(hv + 8); }
.LBB0_794:
	s_or_b64 exec, exec, s[64:65]
	s_waitcnt lgkmcnt(0)
	s_barrier
	ds_read_b32 v0, v29
	ds_read_b32 v1, v28
	ds_read_b128 v[74:77], v30
	s_lshl_b32 s38, s91, 8
	v_lshlrev_b32_e32 v4, 1, v6
	s_waitcnt lgkmcnt(2)
	v_mul_f32_e32 v0, 0xbfb8aa3b, v0
	v_exp_f32_e32 v0, v0
	s_waitcnt lgkmcnt(1)
	v_max_f32_e64 v1, |v1|, |v1|
	s_add_i32 s62, s62, s72
	s_add_i32 s81, s81, s82
	v_max_f32_e32 v73, v1, v0
	v_div_scale_f32 v82, s[64:65], v73, v73, 1.0
	v_rcp_f32_e32 v86, v82
	v_mov_b64_e32 v[0:1], s[44:45]
	v_mad_u64_u32 v[0:1], s[64:65], v14, s88, v[0:1]
	v_fma_f32 v2, -v82, v86, 1.0
	v_fmac_f32_e32 v86, v2, v86
	v_mov_b32_e32 v2, v1
	v_mad_u64_u32 v[2:3], s[64:65], v15, s88, v[2:3]
	v_mov_b32_e32 v1, v2
	v_lshl_add_u64 v[0:1], v[0:1], 0, s[38:39]
	v_lshl_add_u64 v[2:3], v[0:1], 0, v[4:5]
	v_add_co_u32_e32 v0, vcc, s89, v2
	s_cmpk_lt_i32 s62, 0x1000
	s_nop 0
	v_addc_co_u32_e32 v1, vcc, 0, v3, vcc
	v_mov_b32_e32 v78, v220
	v_mov_b32_e32 v79, v221
	v_mov_b32_e32 v80, v222
	v_mov_b32_e32 v81, v223
	v_div_scale_f32 v4, vcc, 1.0, v73, 1.0
	v_mul_f32_e32 v14, v4, v86
	v_fma_f32 v15, -v82, v14, v4
	v_fmac_f32_e32 v14, v15, v86
	v_fma_f32 v4, -v82, v14, v4
	v_div_fmas_f32 v4, v4, v86, v14
	v_div_fixup_f32 v4, v4, v73, 1.0
	v_lshl_add_u64 v[2:3], v[2:3], 0, s[60:61]
	s_waitcnt lgkmcnt(0)
	v_mul_f32_e32 v104, v75, v4
	v_lshlrev_b32_e32 v14, 2, v6
	v_mov_b32_e32 v82, v224
	v_mov_b32_e32 v83, v225
	v_mov_b32_e32 v84, v226
	v_mov_b32_e32 v85, v227
	ds_read_b128 v[86:89], v30 offset:16
	ds_read_b128 v[90:93], v30 offset:32
	ds_read_b128 v[94:97], v30 offset:48
	v_mul_f32_e32 v73, v74, v4
	v_mul_f32_e32 v102, v104, v104
	v_lshl_or_b32 v106, s91, 9, v14
	v_fmac_f32_e32 v102, v73, v73
	v_mul_f32_e32 v105, v4, v76
	global_load_dwordx4 v[98:101], v106, s[52:53]
	v_fmac_f32_e32 v102, v105, v105
	v_mul_f32_e32 v107, v4, v77
	v_fmac_f32_e32 v102, v107, v107
	s_waitcnt lgkmcnt(2)
	v_mul_f32_e32 v108, v4, v86
	v_fmac_f32_e32 v102, v108, v108
	v_mul_f32_e32 v109, v4, v87
	v_fmac_f32_e32 v102, v109, v109
	v_mul_f32_e32 v110, v4, v88
	v_fmac_f32_e32 v102, v110, v110
	v_mul_f32_e32 v111, v4, v89
	s_waitcnt lgkmcnt(1)
	v_pk_mul_f32 v[14:15], v[4:5], v[90:91] op_sel_hi:[0,1]
	v_fmac_f32_e32 v102, v111, v111
	v_pk_mul_f32 v[74:75], v[14:15], v[14:15]
	s_waitcnt lgkmcnt(0)
	v_pk_mul_f32 v[94:95], v[4:5], v[94:95] op_sel_hi:[0,1]
	v_add_f32_e32 v74, v74, v102
	v_pk_mul_f32 v[102:103], v[4:5], v[92:93] op_sel_hi:[0,1]
	v_add_f32_e32 v76, v75, v74
	v_pk_mul_f32 v[74:75], v[102:103], v[102:103]
	v_pk_mul_f32 v[96:97], v[4:5], v[96:97] op_sel_hi:[0,1]
	v_add_f32_e32 v74, v74, v76
	v_add_f32_e32 v76, v75, v74
	v_pk_mul_f32 v[74:75], v[94:95], v[94:95]
	s_waitcnt vmcnt(1)
	v_lshlrev_b32_e32 v112, 16, v82
	v_add_f32_e32 v74, v74, v76
	v_add_f32_e32 v76, v75, v74
	v_pk_mul_f32 v[74:75], v[96:97], v[96:97]
	v_and_b32_e32 v82, 0xffff0000, v82
	v_add_f32_e32 v4, v74, v76
	v_add_f32_e32 v4, v75, v4
	global_load_dwordx4 v[74:77], v106, s[52:53] offset:16
	global_load_dwordx4 v[86:89], v106, s[52:53] offset:48
	global_load_dwordx4 v[90:93], v106, s[52:53] offset:32
	ds_bpermute_b32 v13, v13, v4
	v_lshlrev_b32_e32 v106, 16, v81
	v_and_b32_e32 v81, 0xffff0000, v81
	v_lshlrev_b32_e32 v113, 16, v83
	v_and_b32_e32 v83, 0xffff0000, v83
	s_waitcnt lgkmcnt(0)
	v_add_f32_e32 v4, v4, v13
	ds_bpermute_b32 v13, v71, v4
	v_and_b32_e32 v71, 0xffff0000, v78
	v_mul_f32_e32 v71, 0xbfb8aa3b, v71
	v_exp_f32_e32 v71, v71
	v_lshlrev_b32_e32 v114, 16, v84
	s_waitcnt lgkmcnt(0)
	v_add_f32_e32 v4, v4, v13
	ds_bpermute_b32 v13, v72, v4
	v_lshlrev_b32_e32 v72, 16, v79
	v_mul_f32_e32 v72, 0xbfb8aa3b, v72
	v_exp_f32_e32 v72, v72
	v_add_f32_e32 v71, 1.0, v71
	s_waitcnt lgkmcnt(0)
	v_add_f32_e32 v4, v4, v13
	v_fmamk_f32 v4, v4, 0x3c000000, v64
	v_mul_f32_e32 v13, 0x4b800000, v4
	v_cmp_gt_f32_e32 vcc, s90, v4
	v_rcp_f32_e32 v71, v71
	v_add_f32_e32 v72, 1.0, v72
	v_cndmask_b32_e32 v4, v4, v13, vcc
	v_rsq_f32_e32 v4, v4
	v_rcp_f32_e32 v72, v72
	v_and_b32_e32 v84, 0xffff0000, v84
	v_lshlrev_b32_e32 v115, 16, v85
	v_mul_f32_e32 v13, 0x45800000, v4
	v_cndmask_b32_e32 v4, v4, v13, vcc
	v_lshlrev_b32_e32 v13, 16, v78
	v_mul_f32_e32 v13, 0xbfb8aa3b, v13
	v_exp_f32_e32 v13, v13
	v_and_b32_e32 v78, 0xffff0000, v79
	v_mul_f32_e32 v78, 0xbfb8aa3b, v78
	v_exp_f32_e32 v78, v78
	v_add_f32_e32 v13, 1.0, v13
	v_rcp_f32_e32 v13, v13
	v_mul_f32_e32 v73, v73, v4
	s_waitcnt vmcnt(3)
	v_mul_f32_e32 v73, v98, v73
	v_add_f32_e32 v78, 1.0, v78
	v_mul_f32_e32 v13, v13, v73
	v_mul_f32_e32 v73, v104, v4
	v_mul_f32_e32 v73, v99, v73
	v_mul_f32_e32 v71, v71, v73
	v_mul_f32_e32 v73, v105, v4
	v_rcp_f32_e32 v78, v78
	v_mul_f32_e32 v73, v100, v73
	v_mul_f32_e32 v73, v72, v73
	v_mul_f32_e32 v72, v107, v4
	v_lshlrev_b32_e32 v79, 16, v80
	v_mul_f32_e32 v72, v101, v72
	v_mul_f32_e32 v78, v78, v72
	v_mul_f32_e32 v72, 0xbfb8aa3b, v79
	v_and_b32_e32 v80, 0xffff0000, v80
	v_exp_f32_e32 v72, v72
	v_mul_f32_e32 v80, 0xbfb8aa3b, v80
	v_exp_f32_e32 v80, v80
	v_mul_f32_e32 v79, v108, v4
	v_add_f32_e32 v72, 1.0, v72
	v_rcp_f32_e32 v72, v72
	v_mul_f32_e32 v14, v14, v4
	v_mul_f32_e32 v15, v15, v4
	v_and_b32_e32 v85, 0xffff0000, v85
	s_waitcnt vmcnt(2)
	v_mul_f32_e32 v74, v74, v79
	v_add_f32_e32 v79, 1.0, v80
	v_rcp_f32_e32 v79, v79
	v_mul_f32_e32 v74, v72, v74
	v_mul_f32_e32 v72, v109, v4
	v_mul_f32_e32 v72, v75, v72
	v_mul_f32_e32 v75, v79, v72
	v_mul_f32_e32 v72, 0xbfb8aa3b, v106
	v_exp_f32_e32 v72, v72
	v_mul_f32_e32 v80, 0xbfb8aa3b, v81
	v_exp_f32_e32 v80, v80
	v_mul_f32_e32 v79, v110, v4
	v_add_f32_e32 v72, 1.0, v72
	v_rcp_f32_e32 v72, v72
	v_mul_f32_e32 v76, v76, v79
	v_add_f32_e32 v79, 1.0, v80
	v_rcp_f32_e32 v79, v79
	v_mul_f32_e32 v76, v72, v76
	v_mul_f32_e32 v72, v111, v4
	v_mul_f32_e32 v72, v77, v72
	v_mul_f32_e32 v77, v79, v72
	v_mul_f32_e32 v72, 0xbfb8aa3b, v112
	v_exp_f32_e32 v72, v72
	v_mul_f32_e32 v79, 0xbfb8aa3b, v82
	v_exp_f32_e32 v79, v79
	s_waitcnt vmcnt(0)
; __device__ __forceinline__ bf16_t f2bf(float f) { return (bf16_t)(cvt_pk_bf16(f, 0.f) & 0xffffu); }
; __device__ __forceinline__ float sigmoidf_(float x) { return __builtin_amdgcn_rcpf(1.f + __expf(-x)); }
; __device__ __forceinline__ float logsigmoidf_(float x) { return fminf(x, 0.f) - log1pf(__expf(-fabsf(x))); }
; __device__ __forceinline__ void phase_mlstm_c(const Args& a, unsigned char* lds) {
;     ...
;         const int c = item & 127, h = (item >> 7) & 3, b = item >> 9;
;         const size_t r0 = (size_t)b * SEQ + c * 64;
;         if (wave == 0) {
;             const float ig = SM[(r0 + lane) * 16 + 8 + h] + a.in[I_BI][h];
;             const float lf = logsigmoidf_(SM[(r0 + lane) * 16 + 12 + h] + a.in[I_BF][h]);
;             const float bs = wave_incl_sum(lf, lane);
;             const float av = ig - bs;
;             const float pm = wave_incl_max(av, lane);
;             const float m0 = MS[item];
;             const float mt = bs + fmaxf(pm, m0);
;             bS[lane] = bs; aS[lane] = av; mtS[lane] = mt; wiS[lane] = __expf(bs + m0 - mt);
;             nS[lane] = DN[item * 64 + lane];
;         }
;         { const int s = tid >> 3, d0 = (tid & 7) * 8;
;             *(u32x4*)(QS_ + s * 72 + d0) = *(const u32x4*)(QK + (r0 + s) * 512 + h * 64 + d0);
;             *(u32x4*)(KS + s * 72 + d0) = *(const u32x4*)(QK + (r0 + s) * 512 + 256 + h * 64 + d0); }
;         for (int i = tid; i < 1024; i += 512) { const int s = i >> 4, d0 = (i & 15) * 8; float f[8]; unpack8(*(const u32x4*)(P + (r0 + s) * LDP + C_MV + h * 128 + d0), f);
; #pragma unroll
;             for (int e = 0; e < 8; ++e) BT[(d0 + e) * 136 + s] = f2bf(f[e]); }
;         { const bf16_t* st = ST + (size_t)item * 8192;
;             for (int i = tid; i < 1024; i += 512) { const int dv = i >> 3, k0 = (i & 7) * 8; *(u32x4*)(BT + dv * 136 + 64 + k0) = *(const u32x4*)(st + dv * 64 + k0); } }
;     ...
;             bf16_t* po = P + (r0 + t) * LDP + C_MO + h * 128 + dv0;
;             float og[16]; unpack8(*(const u32x4*)po, og); unpack8(*(const u32x4*)(po + 8), og + 8);
; #pragma unroll
;             for (int e = 0; e < 16; ++e) hv[e] = hv[e] * rs * a.in[I_MHN][h * 128 + dv0 + e] * sigmoidf_(og[e]);
;             *(u32x4*)po = pack8(hv); *(u32x4*)(po + 8) = pack8(hv + 8); }
	v_mul_f32_e32 v14, v90, v14
	v_add_f32_e32 v72, 1.0, v72
	v_rcp_f32_e32 v72, v72
	v_mul_f32_e32 v80, 0xbfb8aa3b, v83
	v_add_f32_e32 v79, 1.0, v79
	v_exp_f32_e32 v80, v80
	v_mul_f32_e32 v14, v72, v14
	v_mul_f32_e32 v72, 0xbfb8aa3b, v113
	v_exp_f32_e32 v72, v72
	v_rcp_f32_e32 v79, v79
	v_mul_f32_e32 v15, v91, v15
	v_add_f32_e32 v80, 1.0, v80
	v_add_f32_e32 v72, 1.0, v72
	v_rcp_f32_e32 v72, v72
	v_mul_f32_e32 v15, v79, v15
	v_mul_f32_e32 v79, v102, v4
	v_rcp_f32_e32 v80, v80
	v_mul_f32_e32 v79, v79, v92
	v_mul_f32_e32 v79, v72, v79
	v_mul_f32_e32 v72, v103, v4
	v_mul_f32_e32 v72, v72, v93
	v_mul_f32_e32 v80, v80, v72
	v_mul_f32_e32 v72, 0xbfb8aa3b, v114
	v_exp_f32_e32 v72, v72
	v_mul_f32_e32 v82, 0xbfb8aa3b, v84
	v_exp_f32_e32 v82, v82
	v_mul_f32_e32 v81, v94, v4
	v_add_f32_e32 v72, 1.0, v72
	v_rcp_f32_e32 v72, v72
	v_add_f32_e32 v82, 1.0, v82
	v_rcp_f32_e32 v82, v82
	v_mul_f32_e32 v81, v81, v86
	v_mul_f32_e32 v81, v72, v81
	v_mul_f32_e32 v72, v95, v4
	v_mul_f32_e32 v72, v72, v87
	v_mul_f32_e32 v82, v82, v72
	v_mul_f32_e32 v72, 0xbfb8aa3b, v115
	v_exp_f32_e32 v72, v72
	v_mul_f32_e32 v84, 0xbfb8aa3b, v85
	v_exp_f32_e32 v84, v84
	v_mul_f32_e32 v83, v96, v4
	v_add_f32_e32 v72, 1.0, v72
	v_rcp_f32_e32 v72, v72
	v_add_f32_e32 v84, 1.0, v84
	v_rcp_f32_e32 v84, v84
	v_mul_f32_e32 v83, v83, v88
	v_mul_f32_e32 v4, v97, v4
	v_mul_f32_e32 v83, v72, v83
	v_mul_f32_e32 v4, v4, v89
	v_cvt_pk_bf16_f32 v72, v13, v71
	v_cvt_pk_bf16_f32 v73, v73, v78
	v_cvt_pk_bf16_f32 v74, v74, v75
	v_cvt_pk_bf16_f32 v75, v76, v77
	v_mul_f32_e32 v4, v84, v4
	global_store_dwordx4 v[0:1], v[72:75], off offset:640
	s_nop 1
	v_cvt_pk_bf16_f32 v72, v14, v15
	v_cvt_pk_bf16_f32 v73, v79, v80
	v_cvt_pk_bf16_f32 v74, v81, v82
	v_cvt_pk_bf16_f32 v75, v83, v4
	global_store_dwordx4 v[2:3], v[72:75], off offset:16
	s_barrier
	s_cbranch_scc0 .LBB0_855
.LBB0_795:
	s_ashr_i32 s64, s62, 9
	s_ashr_i32 s65, s64, 31
	s_lshl_b32 s92, s62, 6
	s_lshl_b64 s[64:65], s[64:65], 13
	s_and_b32 s33, s92, 0x1fc0
	s_ashr_i32 s63, s62, 31
	s_bfe_u32 s91, s62, 0x20007
	s_or_b32 s66, s64, s33
	s_mov_b32 s67, s65
	v_lshl_add_u64 v[252:253], s[66:67], 0, v[128:129]
	v_mov_b64_e32 v[248:249], s[44:45]
	v_mov_b32_e32 v251, v5
	v_mad_u64_u32 v[248:249], vcc, v252, s88, v[248:249]
	s_lshl_b32 s38, s91, 8
	v_mov_b32_e32 v250, v249
	v_mad_u64_u32 v[250:251], vcc, v253, s88, v[250:251]
	s_nop 0
	v_mov_b32_e32 v249, v250
	v_lshl_add_u64 v[248:249], v[248:249], 0, s[38:39]
	v_lshlrev_b32_e32 v250, 1, v6
	v_mov_b32_e32 v251, v5
	v_lshl_add_u64 v[250:251], v[248:249], 0, v[250:251]
	v_add_co_u32_e32 v248, vcc, s89, v250
	s_nop 1
	v_addc_co_u32_e32 v249, vcc, 0, v251, vcc
	global_load_dwordx4 v[220:223], v[248:249], off offset:640
	v_lshl_add_u64 v[252:253], v[250:251], 0, s[60:61]
	global_load_dwordx4 v[224:227], v[252:253], off offset:16
	s_nop 0
	v_lshl_add_u64 v[252:253], s[66:67], 0, v[128:129]
	v_lshlrev_b64 v[252:253], 10, v[252:253]
	v_lshl_add_u64 v[252:253], s[0:1], 0, v[252:253]
	s_lshl_b32 s38, s91, 7
	v_lshl_add_u64 v[252:253], v[252:253], 0, s[38:39]
	v_mov_b32_e32 v251, v5
	v_mov_b32_e32 v250, v12
	v_lshl_add_u64 v[252:253], v[252:253], 0, v[250:251]
	global_load_dwordx4 v[228:231], v[252:253], off
	global_load_dwordx4 v[232:235], v[252:253], off offset:512
	s_lshr_b32 s33, s62, 7
	s_and_b32 s38, s81, 0x1fc0
	s_and_b32 s33, s33, 3
	s_add_u32 s64, s38, s64
	s_addc_u32 s65, 0, s65
	v_lshl_add_u64 v[252:253], s[64:65], 0, v[16:17]
	v_mad_u64_u32 v[250:251], vcc, v252, s88, 0
	v_mad_i32_i24 v253, v253, s88, v251
	v_lshl_or_b32 v252, s33, 8, v250
	v_lshl_add_u64 v[252:253], v[8:9], 0, v[252:253]
	s_lshl_b64 s[94:95], s[62:63], 14
	global_load_dwordx4 v[236:239], v[252:253], off
	s_nop 0
	v_lshl_add_u64 v[252:253], v[252:253], 0, s[40:41]
	global_load_dwordx4 v[240:243], v[252:253], off
	s_nop 0
	v_lshl_add_u64 v[252:253], v[10:11], 0, s[94:95]
	global_load_dwordx4 v[244:247], v[252:253], off
	s_nop 0
	v_lshl_add_u64 v[252:253], v[252:253], 0, s[42:43]
	global_load_dwordx4 v[248:251], v[252:253], off
	s_and_saveexec_b64 s[76:77], s[4:5]
	s_cbranch_execz .LBB0_797
; __device__ __forceinline__ float logsigmoidf_(float x) { return fminf(x, 0.f) - log1pf(__expf(-fabsf(x))); }
; __device__ __forceinline__ void phase_mlstm_c(const Args& a, unsigned char* lds) {
;     ...
;         if (wave == 0) {
;             const float ig = SM[(r0 + lane) * 16 + 8 + h] + a.in[I_BI][h];
;             const float lf = logsigmoidf_(SM[(r0 + lane) * 16 + 12 + h] + a.in[I_BF][h]);
;             const float bs = wave_incl_sum(lf, lane);
;             const float av = ig - bs;
;             const float pm = wave_incl_max(av, lane);
;             const float m0 = MS[item];
;             const float mt = bs + fmaxf(pm, m0);
;             bS[lane] = bs; aS[lane] = av; mtS[lane] = mt; wiS[lane] = __expf(bs + m0 - mt);
;             nS[lane] = DN[item * 64 + lane];
	v_mov_b32_e32 v1, s67
	v_or_b32_e32 v0, s66, v156
	v_lshlrev_b64 v[0:1], 6, v[0:1]
	v_lshl_add_u64 v[0:1], s[58:59], 0, v[0:1]
	s_lshl_b32 s38, s91, 2
	v_lshl_add_u64 v[0:1], v[0:1], 0, s[38:39]
	v_mov_b32_e32 v2, s38
	global_load_dword v3, v[0:1], off offset:48
	global_load_dword v4, v2, s[50:51]
	s_nop 0
	global_load_dword v2, v2, s[48:49]
	s_nop 0
	global_load_dword v13, v[0:1], off offset:32
	s_lshl_b64 s[94:95], s[62:63], 2
	v_or_b32_e32 v0, s92, v156
	s_add_u32 s92, s78, s94
	v_ashrrev_i32_e32 v1, 31, v0
	s_addc_u32 s93, s79, s95
	v_lshl_add_u64 v[0:1], v[0:1], 2, s[36:37]
	global_load_dword v77, v5, s[92:93]
	global_load_dword v78, v[0:1], off
	v_mov_b32_e32 v14, v5
	v_mov_b32_e32 v15, v5
	v_mov_b32_e32 v71, 0xff800000
	v_mov_b32_e32 v72, 0xff800000
	v_mov_b32_e32 v73, 0xff800000
	v_mov_b32_e32 v74, 0xff800000
	v_mov_b32_e32 v75, 0xff800000
	v_mov_b32_e32 v76, 0xff800000
	s_waitcnt vmcnt(4)
	v_add_f32_e32 v3, v3, v4
	v_mul_f32_e64 v4, |v3|, s83
	v_exp_f32_e32 v4, v4
	s_waitcnt vmcnt(2)
	v_add_f32_e32 v2, v13, v2
	v_min_f32_e32 v3, 0, v3
	v_add_f32_e32 v13, 1.0, v4
	v_add_f32_e32 v79, -1.0, v13
	v_frexp_mant_f32_e32 v80, v13
	v_cvt_f64_f32_e32 v[0:1], v13
	v_sub_f32_e32 v81, v79, v13
	v_frexp_exp_i32_f64_e32 v0, v[0:1]
	v_cmp_gt_f32_e32 vcc, s84, v80
	v_sub_f32_e32 v79, v4, v79
	v_add_f32_e32 v1, 1.0, v81
	v_subbrev_co_u32_e32 v0, vcc, 0, v0, vcc
	v_add_f32_e32 v1, v79, v1
	v_sub_u32_e32 v79, 0, v0
	v_cvt_f32_i32_e32 v0, v0
	v_ldexp_f32 v13, v13, v79
	v_ldexp_f32 v1, v1, v79
	v_add_f32_e32 v79, -1.0, v13
	v_add_f32_e32 v80, 1.0, v13
	v_add_f32_e32 v81, 1.0, v79
	v_add_f32_e32 v82, -1.0, v80
	v_sub_f32_e32 v81, v13, v81
	v_sub_f32_e32 v13, v13, v82
	v_mul_f32_e32 v82, 0x3f317218, v0
	v_add_f32_e32 v81, v1, v81
	v_add_f32_e32 v1, v1, v13
	v_fma_f32 v13, v0, s85, -v82
	v_add_f32_e32 v83, v79, v81
	v_add_f32_e32 v84, v80, v1
	v_fmac_f32_e32 v13, 0xb102e308, v0
	v_sub_f32_e32 v0, v83, v79
	v_sub_f32_e32 v79, v84, v80
	v_rcp_f32_e32 v80, v84
	v_add_f32_e32 v85, v82, v13
	v_sub_f32_e32 v1, v1, v79
	v_sub_f32_e32 v79, v85, v82
	v_sub_f32_e32 v13, v13, v79
	v_mul_f32_e32 v79, v83, v80
	v_sub_f32_e32 v0, v81, v0
	v_mul_f32_e32 v81, v84, v79
	v_fma_f32 v82, v79, v84, -v81
	v_fmac_f32_e32 v82, v79, v1
	v_add_f32_e32 v86, v81, v82
	v_sub_f32_e32 v87, v83, v86
	v_sub_f32_e32 v81, v86, v81
	v_sub_f32_e32 v83, v83, v87
	v_sub_f32_e32 v81, v81, v82
	v_sub_f32_e32 v82, v83, v86
	v_add_f32_e32 v0, v0, v82
	v_add_f32_e32 v0, v81, v0
	v_add_f32_e32 v81, v87, v0
	v_mul_f32_e32 v82, v80, v81
	v_sub_f32_e32 v83, v87, v81
	v_mul_f32_e32 v86, v84, v82
	v_add_f32_e32 v0, v0, v83
	v_add_f32_e32 v83, v79, v82
	v_fma_f32 v84, v82, v84, -v86
	v_sub_f32_e32 v79, v83, v79
	v_fmac_f32_e32 v84, v82, v1
	v_sub_f32_e32 v1, v82, v79
	v_add_f32_e32 v79, v86, v84
	v_sub_f32_e32 v82, v79, v86
	v_sub_f32_e32 v86, v81, v79
	v_sub_f32_e32 v81, v81, v86
	v_sub_f32_e32 v79, v81, v79
	v_sub_f32_e32 v82, v82, v84
	v_add_f32_e32 v0, v0, v79
	v_add_f32_e32 v0, v82, v0
	v_add_f32_e32 v0, v86, v0
	v_mul_f32_e32 v0, v80, v0
	v_add_f32_e32 v0, v1, v0
	v_add_f32_e32 v1, v83, v0
	v_mul_f32_e32 v79, v1, v1
	v_fmamk_f32 v82, v79, 0x3e9b6dac, v61
	v_sub_f32_e32 v80, v1, v83
	v_ldexp_f32 v81, v1, 1
	v_mul_f32_e32 v1, v1, v79
	v_fmaak_f32 v79, v79, v82, 0x3f2aaada
	v_mul_f32_e32 v1, v1, v79
	v_add_f32_e32 v79, v81, v1
	v_sub_f32_e32 v0, v0, v80
	v_sub_f32_e32 v80, v79, v81
	v_ldexp_f32 v0, v0, 1
	v_sub_f32_e32 v1, v1, v80
	v_add_f32_e32 v0, v0, v1
	v_add_f32_e32 v1, v79, v0
	v_sub_f32_e32 v79, v1, v79
	v_add_f32_e32 v80, v85, v1
	v_sub_f32_e32 v0, v0, v79
	v_sub_f32_e32 v79, v80, v85
	v_sub_f32_e32 v81, v80, v79
	v_sub_f32_e32 v1, v1, v79
	v_add_f32_e32 v79, v13, v0
	v_sub_f32_e32 v81, v85, v81
	v_sub_f32_e32 v82, v79, v13
	v_add_f32_e32 v1, v1, v81
	v_sub_f32_e32 v81, v79, v82
	v_sub_f32_e32 v0, v0, v82
	v_sub_f32_e32 v13, v13, v81
	v_add_f32_e32 v1, v79, v1
	v_add_f32_e32 v0, v0, v13
	v_add_f32_e32 v13, v80, v1
	v_sub_f32_e32 v79, v13, v80
	v_sub_f32_e32 v1, v1, v79
	v_add_f32_e32 v0, v0, v1
	v_add_f32_e32 v0, v13, v0
	v_cmp_neq_f32_e32 vcc, s86, v4
	s_nop 1
	v_cndmask_b32_e32 v0, v65, v0, vcc
	v_cmp_ngt_f32_e32 vcc, -1.0, v4
	s_nop 1
	v_cndmask_b32_e32 v0, v66, v0, vcc
	v_cmp_neq_f32_e32 vcc, -1.0, v4
	s_nop 1
	v_cndmask_b32_e32 v0, v62, v0, vcc
	v_cmp_lt_f32_e64 vcc, |v4|, s87
	s_nop 1
	v_cndmask_b32_e32 v0, v0, v4, vcc
	v_sub_f32_e32 v0, v3, v0
	s_nop 1
	v_add_f32_dpp v0, v0, v0 row_shr:1 row_mask:0xf bank_mask:0xf bound_ctrl:1
	s_nop 1
	v_add_f32_dpp v0, v0, v0 row_shr:2 row_mask:0xf bank_mask:0xf bound_ctrl:1
	s_nop 1
	v_add_f32_dpp v0, v0, v0 row_shr:4 row_mask:0xf bank_mask:0xf bound_ctrl:1
	s_nop 1
	v_add_f32_dpp v0, v0, v0 row_shr:8 row_mask:0xf bank_mask:0xf bound_ctrl:1
	s_nop 1
	v_mov_b32_dpp v14, v0 row_bcast:15 row_mask:0xa bank_mask:0xf
	v_add_f32_e32 v0, v0, v14
	s_nop 1
	v_mov_b32_dpp v15, v0 row_bcast:31 row_mask:0xc bank_mask:0xf
	v_add_f32_e32 v0, v0, v15
	v_sub_f32_e32 v1, v2, v0
	s_waitcnt vmcnt(1)
	v_add_f32_e32 v2, v77, v0
	v_mov_b32_dpp v71, v1 row_shr:1 row_mask:0xf bank_mask:0xf
	v_max_f32_e32 v3, v71, v71
	v_max_f32_e32 v3, v1, v3
	s_nop 1
	v_mov_b32_dpp v72, v3 row_shr:2 row_mask:0xf bank_mask:0xf
	v_max_f32_e32 v4, v72, v72
	v_max_f32_e32 v3, v3, v4
	s_nop 1
	v_mov_b32_dpp v73, v3 row_shr:4 row_mask:0xf bank_mask:0xf
	v_max_f32_e32 v4, v73, v73
	v_max_f32_e32 v3, v3, v4
	s_nop 1
	v_mov_b32_dpp v74, v3 row_shr:8 row_mask:0xf bank_mask:0xf
	v_max_f32_e32 v4, v74, v74
	v_max_f32_e32 v3, v3, v4
	s_nop 1
	v_mov_b32_dpp v75, v3 row_bcast:15 row_mask:0xa bank_mask:0xf
	v_max_f32_e32 v4, v75, v75
	v_max_f32_e32 v3, v3, v4
	s_nop 1
	v_mov_b32_dpp v76, v3 row_bcast:31 row_mask:0xc bank_mask:0xf
	v_max3_f32 v3, v3, v76, v77
	v_add_f32_e32 v3, v0, v3
	v_sub_f32_e32 v2, v2, v3
	v_mul_f32_e32 v2, 0x3fb8aa3b, v2
	v_exp_f32_e32 v2, v2
	ds_write_b32 v7, v0
	ds_write_b32 v18, v1
	ds_write_b32 v19, v3
	ds_write_b32 v20, v2
	s_waitcnt vmcnt(0)
	ds_write_b32 v21, v78
